# rw_scan inner loop hand-scheduled: DPP wait states filled with independent work, staging moved mid-iteration
# speedup vs baseline: 1.0267x; 1.0267x over previous
.LBB0_773:
	v_cndmask_b32_e64 v13, v14, v13, s[44:45]
	v_add_f32_e32 v13, v13, v15
	v_cvt_pk_bf16_f32 v14, v13, s0
	v_ashrrev_i32_e32 v13, 31, v12
	v_lshlrev_b64 v[12:13], 11, v[12:13]
	v_lshl_add_u64 v[12:13], v[56:57], 0, v[12:13]
	global_store_short v[12:13], v14, off
	s_add_i32 s6, s6, 16
	s_add_i32 s10, s10, 1
	v_add_u32_e32 v101, -16, v101
	s_cmpk_eq_i32 s6, 0x20f0
	v_add_u32_e32 v100, -16, v100
	s_waitcnt lgkmcnt(0)
	s_barrier
	s_cbranch_scc1 .LBB0_767
.LBB0_774:
	v_add_u32_e32 v12, s6, v49
	v_add_u32_e32 v13, 16, v12
	v_cmp_gt_i32_e32 vcc, s16, v13
	v_add_u32_e32 v12, 0xffffff10, v12
	s_and_b32 s11, s10, 1
	v_cndmask_b32_e32 v14, v113, v114, vcc
	v_cndmask_b32_e32 v12, v12, v13, vcc
	v_add_u32_e32 v14, v14, v100
	v_cndmask_b32_e32 v13, v98, v99, vcc
	v_cndmask_b32_e64 v12, v14, v12, s[46:47]
	v_add_u32_e32 v12, v12, v13
	v_ashrrev_i32_e32 v13, 31, v12
	v_lshlrev_b64 v[14:15], 11, v[12:13]
	v_lshl_or_b32 v16, v58, 1, v14
	v_mov_b32_e32 v17, v15
	v_lshl_add_u64 v[18:19], s[2:3], 0, v[16:17]
	v_lshl_or_b32 v12, v12, 4, s9
	global_load_dwordx2 v[74:75], v[18:19], off
	v_lshl_add_u64 v[18:19], s[90:91], 0, v[16:17]
	v_ashrrev_i32_e32 v13, 31, v12
	s_mul_i32 s0, s11, 0x5400
	global_load_dwordx2 v[62:63], v[18:19], off
	v_lshl_add_u64 v[18:19], s[20:21], 0, v[16:17]
	v_lshl_add_u64 v[16:17], s[24:25], 0, v[16:17]
	v_lshl_add_u64 v[12:13], v[12:13], 2, s[74:75]
	s_add_i32 s0, s0, 16
	global_load_dwordx2 v[76:77], v[16:17], off
	global_load_dword v78, v[12:13], off
	v_lshl_add_u64 v[12:13], v[60:61], 0, v[14:15]
	v_lshl_add_u32 v126, v87, 2, s0
	global_load_dwordx2 v[72:73], v[18:19], off
	global_load_ushort v102, v[12:13], off
	v_add3_u32 v124, s0, v91, v92
	ds_read_b32 v204, v124 offset:1280
	ds_read_b128 v[184:187], v126 offset:0
	ds_read_b128 v[196:199], v126 offset:768
	ds_read_b128 v[188:191], v126 offset:256
	ds_read_b128 v[200:203], v126 offset:1024
	ds_read_b128 v[192:195], v126 offset:512
	ds_read_b32 v226, v124 offset:2624
	ds_read_b128 v[206:209], v126 offset:1344
	ds_read_b128 v[218:221], v126 offset:2112
	ds_read_b128 v[210:213], v126 offset:1600
	ds_read_b128 v[222:225], v126 offset:2368
	ds_read_b128 v[214:217], v126 offset:1856
	s_waitcnt lgkmcnt(6)
	v_pk_mul_f32 v[250:251], v[8:9], v[184:185]
	v_pk_mul_f32 v[252:253], v[204:205], v[196:197] op_sel_hi:[0,1]
	v_pk_fma_f32 v[250:251], v[10:11], v[186:187], v[250:251]
	v_pk_mul_f32 v[254:255], v[204:205], v[198:199] op_sel_hi:[0,1]
	v_add_f32_e32 v14, v250, v251
	v_pk_fma_f32 v[252:253], v[8:9], v[188:189], v[252:253]
	v_pk_fma_f32 v[254:255], v[10:11], v[190:191], v[254:255]
	v_add_f32_dpp v14, v14, v14 quad_perm:[1,0,3,2] row_mask:0xf bank_mask:0xf bound_ctrl:1
	ds_read_b32 v248, v124 offset:3968
	ds_read_b128 v[228:231], v126 offset:2688
	v_add_f32_dpp v14, v14, v14 quad_perm:[2,3,0,1] row_mask:0xf bank_mask:0xf bound_ctrl:1
	ds_read_b128 v[240:243], v126 offset:3456
	ds_read_b128 v[232:235], v126 offset:2944
	v_add_f32_dpp v14, v14, v14 row_half_mirror row_mask:0xf bank_mask:0xf bound_ctrl:1
	ds_read_b128 v[244:247], v126 offset:3712
	ds_read_b128 v[236:239], v126 offset:3200
	v_add_f32_dpp v14, v14, v14 row_mirror row_mask:0xf bank_mask:0xf bound_ctrl:1
	v_pk_fma_f32 v[8:9], v[14:15], v[192:193], v[252:253] op_sel_hi:[0,1,1]
	v_pk_fma_f32 v[10:11], v[14:15], v[194:195], v[254:255] op_sel_hi:[0,1,1]
	s_waitcnt lgkmcnt(6)
	v_pk_mul_f32 v[250:251], v[8:9], v[206:207]
	v_pk_mul_f32 v[252:253], v[226:227], v[218:219] op_sel_hi:[0,1]
	v_pk_fma_f32 v[250:251], v[10:11], v[208:209], v[250:251]
	v_pk_mul_f32 v[254:255], v[226:227], v[220:221] op_sel_hi:[0,1]
	v_add_f32_e32 v14, v250, v251
	v_pk_fma_f32 v[252:253], v[8:9], v[210:211], v[252:253]
	v_pk_fma_f32 v[254:255], v[10:11], v[212:213], v[254:255]
	v_add_f32_dpp v14, v14, v14 quad_perm:[1,0,3,2] row_mask:0xf bank_mask:0xf bound_ctrl:1
	v_pk_mul_f32 v[12:13], v[8:9], v[200:201]
	ds_read_b32 v204, v124 offset:5312
	v_add_f32_dpp v14, v14, v14 quad_perm:[2,3,0,1] row_mask:0xf bank_mask:0xf bound_ctrl:1
	v_pk_fma_f32 v[12:13], v[10:11], v[202:203], v[12:13]
	ds_read_b128 v[184:187], v126 offset:4032
	v_add_f32_dpp v14, v14, v14 row_half_mirror row_mask:0xf bank_mask:0xf bound_ctrl:1
	v_add_f32_e32 v18, v12, v13
	ds_read_b128 v[196:199], v126 offset:4800
	v_add_f32_dpp v14, v14, v14 row_mirror row_mask:0xf bank_mask:0xf bound_ctrl:1
	v_pk_fma_f32 v[8:9], v[14:15], v[214:215], v[252:253] op_sel_hi:[0,1,1]
	v_pk_fma_f32 v[10:11], v[14:15], v[216:217], v[254:255] op_sel_hi:[0,1,1]
	ds_read_b128 v[188:191], v126 offset:4288
	ds_read_b128 v[200:203], v126 offset:5056
	ds_read_b128 v[192:195], v126 offset:4544
	s_waitcnt lgkmcnt(6)
	v_pk_mul_f32 v[250:251], v[8:9], v[228:229]
	v_pk_mul_f32 v[252:253], v[248:249], v[240:241] op_sel_hi:[0,1]
	v_pk_fma_f32 v[250:251], v[10:11], v[230:231], v[250:251]
	v_pk_mul_f32 v[254:255], v[248:249], v[242:243] op_sel_hi:[0,1]
	v_add_f32_e32 v14, v250, v251
	v_pk_fma_f32 v[252:253], v[8:9], v[232:233], v[252:253]
	v_pk_fma_f32 v[254:255], v[10:11], v[234:235], v[254:255]
	v_add_f32_dpp v14, v14, v14 quad_perm:[1,0,3,2] row_mask:0xf bank_mask:0xf bound_ctrl:1
	v_pk_mul_f32 v[12:13], v[8:9], v[222:223]
	ds_read_b32 v226, v124 offset:6656
	v_add_f32_dpp v14, v14, v14 quad_perm:[2,3,0,1] row_mask:0xf bank_mask:0xf bound_ctrl:1
	v_pk_fma_f32 v[12:13], v[10:11], v[224:225], v[12:13]
	ds_read_b128 v[206:209], v126 offset:5376
	v_add_f32_dpp v14, v14, v14 row_half_mirror row_mask:0xf bank_mask:0xf bound_ctrl:1
	v_add_f32_e32 v19, v12, v13
	ds_read_b128 v[218:221], v126 offset:6144
	v_add_f32_dpp v14, v14, v14 row_mirror row_mask:0xf bank_mask:0xf bound_ctrl:1
	v_pk_fma_f32 v[8:9], v[14:15], v[236:237], v[252:253] op_sel_hi:[0,1,1]
	v_pk_fma_f32 v[10:11], v[14:15], v[238:239], v[254:255] op_sel_hi:[0,1,1]
	ds_read_b128 v[210:213], v126 offset:5632
	ds_read_b128 v[222:225], v126 offset:6400
	ds_read_b128 v[214:217], v126 offset:5888
	s_waitcnt lgkmcnt(6)
	v_pk_mul_f32 v[250:251], v[8:9], v[184:185]
	v_pk_mul_f32 v[252:253], v[204:205], v[196:197] op_sel_hi:[0,1]
	v_pk_fma_f32 v[250:251], v[10:11], v[186:187], v[250:251]
	v_pk_mul_f32 v[254:255], v[204:205], v[198:199] op_sel_hi:[0,1]
	v_add_f32_e32 v14, v250, v251
	v_pk_fma_f32 v[252:253], v[8:9], v[188:189], v[252:253]
	v_pk_fma_f32 v[254:255], v[10:11], v[190:191], v[254:255]
	v_add_f32_dpp v14, v14, v14 quad_perm:[1,0,3,2] row_mask:0xf bank_mask:0xf bound_ctrl:1
	v_pk_mul_f32 v[12:13], v[8:9], v[244:245]
	ds_read_b32 v248, v124 offset:8000
	v_add_f32_dpp v14, v14, v14 quad_perm:[2,3,0,1] row_mask:0xf bank_mask:0xf bound_ctrl:1
	v_pk_fma_f32 v[12:13], v[10:11], v[246:247], v[12:13]
	ds_read_b128 v[228:231], v126 offset:6720
	v_add_f32_dpp v14, v14, v14 row_half_mirror row_mask:0xf bank_mask:0xf bound_ctrl:1
	v_add_f32_e32 v20, v12, v13
	ds_read_b128 v[240:243], v126 offset:7488
	v_add_f32_dpp v14, v14, v14 row_mirror row_mask:0xf bank_mask:0xf bound_ctrl:1
	v_pk_fma_f32 v[8:9], v[14:15], v[192:193], v[252:253] op_sel_hi:[0,1,1]
	v_pk_fma_f32 v[10:11], v[14:15], v[194:195], v[254:255] op_sel_hi:[0,1,1]
	ds_read_b128 v[232:235], v126 offset:6976
	ds_read_b128 v[244:247], v126 offset:7744
	ds_read_b128 v[236:239], v126 offset:7232
	s_waitcnt lgkmcnt(6)
	v_pk_mul_f32 v[250:251], v[8:9], v[206:207]
	v_pk_mul_f32 v[252:253], v[226:227], v[218:219] op_sel_hi:[0,1]
	v_pk_fma_f32 v[250:251], v[10:11], v[208:209], v[250:251]
	v_pk_mul_f32 v[254:255], v[226:227], v[220:221] op_sel_hi:[0,1]
	v_add_f32_e32 v14, v250, v251
	v_pk_fma_f32 v[252:253], v[8:9], v[210:211], v[252:253]
	v_pk_fma_f32 v[254:255], v[10:11], v[212:213], v[254:255]
	v_add_f32_dpp v14, v14, v14 quad_perm:[1,0,3,2] row_mask:0xf bank_mask:0xf bound_ctrl:1
	v_pk_mul_f32 v[12:13], v[8:9], v[200:201]
	ds_read_b32 v204, v124 offset:9344
	v_add_f32_dpp v14, v14, v14 quad_perm:[2,3,0,1] row_mask:0xf bank_mask:0xf bound_ctrl:1
	v_pk_fma_f32 v[12:13], v[10:11], v[202:203], v[12:13]
	ds_read_b128 v[184:187], v126 offset:8064
	v_add_f32_dpp v14, v14, v14 row_half_mirror row_mask:0xf bank_mask:0xf bound_ctrl:1
	v_add_f32_e32 v21, v12, v13
	ds_read_b128 v[196:199], v126 offset:8832
	v_add_f32_dpp v14, v14, v14 row_mirror row_mask:0xf bank_mask:0xf bound_ctrl:1
	v_pk_fma_f32 v[8:9], v[14:15], v[214:215], v[252:253] op_sel_hi:[0,1,1]
	v_pk_fma_f32 v[10:11], v[14:15], v[216:217], v[254:255] op_sel_hi:[0,1,1]
	ds_read_b128 v[188:191], v126 offset:8320
	ds_read_b128 v[200:203], v126 offset:9088
	ds_read_b128 v[192:195], v126 offset:8576
	s_waitcnt lgkmcnt(6)
	v_pk_mul_f32 v[250:251], v[8:9], v[228:229]
	v_pk_mul_f32 v[252:253], v[248:249], v[240:241] op_sel_hi:[0,1]
	v_pk_fma_f32 v[250:251], v[10:11], v[230:231], v[250:251]
	v_pk_mul_f32 v[254:255], v[248:249], v[242:243] op_sel_hi:[0,1]
	v_add_f32_e32 v14, v250, v251
	v_pk_fma_f32 v[252:253], v[8:9], v[232:233], v[252:253]
	v_pk_fma_f32 v[254:255], v[10:11], v[234:235], v[254:255]
	v_add_f32_dpp v14, v14, v14 quad_perm:[1,0,3,2] row_mask:0xf bank_mask:0xf bound_ctrl:1
	v_pk_mul_f32 v[12:13], v[8:9], v[222:223]
	ds_read_b32 v226, v124 offset:10688
	v_add_f32_dpp v14, v14, v14 quad_perm:[2,3,0,1] row_mask:0xf bank_mask:0xf bound_ctrl:1
	v_pk_fma_f32 v[12:13], v[10:11], v[224:225], v[12:13]
	ds_read_b128 v[206:209], v126 offset:9408
	v_add_f32_dpp v14, v14, v14 row_half_mirror row_mask:0xf bank_mask:0xf bound_ctrl:1
	v_add_f32_e32 v22, v12, v13
	ds_read_b128 v[218:221], v126 offset:10176
	v_add_f32_dpp v14, v14, v14 row_mirror row_mask:0xf bank_mask:0xf bound_ctrl:1
	v_pk_fma_f32 v[8:9], v[14:15], v[236:237], v[252:253] op_sel_hi:[0,1,1]
	v_pk_fma_f32 v[10:11], v[14:15], v[238:239], v[254:255] op_sel_hi:[0,1,1]
	ds_read_b128 v[210:213], v126 offset:9664
	ds_read_b128 v[222:225], v126 offset:10432
	ds_read_b128 v[214:217], v126 offset:9920
	s_waitcnt lgkmcnt(6)
	v_pk_mul_f32 v[250:251], v[8:9], v[184:185]
	v_pk_mul_f32 v[252:253], v[204:205], v[196:197] op_sel_hi:[0,1]
	v_pk_fma_f32 v[250:251], v[10:11], v[186:187], v[250:251]
	v_pk_mul_f32 v[254:255], v[204:205], v[198:199] op_sel_hi:[0,1]
	v_add_f32_e32 v14, v250, v251
	v_pk_fma_f32 v[252:253], v[8:9], v[188:189], v[252:253]
	v_pk_fma_f32 v[254:255], v[10:11], v[190:191], v[254:255]
	v_add_f32_dpp v14, v14, v14 quad_perm:[1,0,3,2] row_mask:0xf bank_mask:0xf bound_ctrl:1
	v_pk_mul_f32 v[12:13], v[8:9], v[244:245]
	ds_read_b32 v248, v124 offset:12032
	v_add_f32_dpp v14, v14, v14 quad_perm:[2,3,0,1] row_mask:0xf bank_mask:0xf bound_ctrl:1
	v_pk_fma_f32 v[12:13], v[10:11], v[246:247], v[12:13]
	ds_read_b128 v[228:231], v126 offset:10752
	v_add_f32_dpp v14, v14, v14 row_half_mirror row_mask:0xf bank_mask:0xf bound_ctrl:1
	v_add_f32_e32 v23, v12, v13
	ds_read_b128 v[240:243], v126 offset:11520
	v_add_f32_dpp v14, v14, v14 row_mirror row_mask:0xf bank_mask:0xf bound_ctrl:1
	v_pk_fma_f32 v[8:9], v[14:15], v[192:193], v[252:253] op_sel_hi:[0,1,1]
	v_pk_fma_f32 v[10:11], v[14:15], v[194:195], v[254:255] op_sel_hi:[0,1,1]
	ds_read_b128 v[232:235], v126 offset:11008
	ds_read_b128 v[244:247], v126 offset:11776
	ds_read_b128 v[236:239], v126 offset:11264
	s_waitcnt lgkmcnt(6)
	v_pk_mul_f32 v[250:251], v[8:9], v[206:207]
	v_pk_mul_f32 v[252:253], v[226:227], v[218:219] op_sel_hi:[0,1]
	v_pk_fma_f32 v[250:251], v[10:11], v[208:209], v[250:251]
	v_pk_mul_f32 v[254:255], v[226:227], v[220:221] op_sel_hi:[0,1]
	v_add_f32_e32 v14, v250, v251
	v_pk_fma_f32 v[252:253], v[8:9], v[210:211], v[252:253]
	v_pk_fma_f32 v[254:255], v[10:11], v[212:213], v[254:255]
	v_add_f32_dpp v14, v14, v14 quad_perm:[1,0,3,2] row_mask:0xf bank_mask:0xf bound_ctrl:1
	v_pk_mul_f32 v[12:13], v[8:9], v[200:201]
	ds_read_b32 v204, v124 offset:13376
	v_add_f32_dpp v14, v14, v14 quad_perm:[2,3,0,1] row_mask:0xf bank_mask:0xf bound_ctrl:1
	v_pk_fma_f32 v[12:13], v[10:11], v[202:203], v[12:13]
	ds_read_b128 v[184:187], v126 offset:12096
	v_add_f32_dpp v14, v14, v14 row_half_mirror row_mask:0xf bank_mask:0xf bound_ctrl:1
	v_add_f32_e32 v24, v12, v13
	ds_read_b128 v[196:199], v126 offset:12864
	v_add_f32_dpp v14, v14, v14 row_mirror row_mask:0xf bank_mask:0xf bound_ctrl:1
	v_pk_fma_f32 v[8:9], v[14:15], v[214:215], v[252:253] op_sel_hi:[0,1,1]
	v_pk_fma_f32 v[10:11], v[14:15], v[216:217], v[254:255] op_sel_hi:[0,1,1]
	ds_read_b128 v[188:191], v126 offset:12352
	ds_read_b128 v[200:203], v126 offset:13120
	ds_read_b128 v[192:195], v126 offset:12608
	s_waitcnt lgkmcnt(6)
	v_pk_mul_f32 v[250:251], v[8:9], v[228:229]
	v_pk_mul_f32 v[252:253], v[248:249], v[240:241] op_sel_hi:[0,1]
	v_pk_fma_f32 v[250:251], v[10:11], v[230:231], v[250:251]
	v_pk_mul_f32 v[254:255], v[248:249], v[242:243] op_sel_hi:[0,1]
	v_add_f32_e32 v14, v250, v251
	v_pk_fma_f32 v[252:253], v[8:9], v[232:233], v[252:253]
	v_pk_fma_f32 v[254:255], v[10:11], v[234:235], v[254:255]
	v_add_f32_dpp v14, v14, v14 quad_perm:[1,0,3,2] row_mask:0xf bank_mask:0xf bound_ctrl:1
	v_pk_mul_f32 v[12:13], v[8:9], v[222:223]
	ds_read_b32 v226, v124 offset:14720
	v_add_f32_dpp v14, v14, v14 quad_perm:[2,3,0,1] row_mask:0xf bank_mask:0xf bound_ctrl:1
	v_pk_fma_f32 v[12:13], v[10:11], v[224:225], v[12:13]
	ds_read_b128 v[206:209], v126 offset:13440
	v_add_f32_dpp v14, v14, v14 row_half_mirror row_mask:0xf bank_mask:0xf bound_ctrl:1
	v_add_f32_e32 v25, v12, v13
	ds_read_b128 v[218:221], v126 offset:14208
	v_add_f32_dpp v14, v14, v14 row_mirror row_mask:0xf bank_mask:0xf bound_ctrl:1
	v_pk_fma_f32 v[8:9], v[14:15], v[236:237], v[252:253] op_sel_hi:[0,1,1]
	v_pk_fma_f32 v[10:11], v[14:15], v[238:239], v[254:255] op_sel_hi:[0,1,1]
	ds_read_b128 v[210:213], v126 offset:13696
	ds_read_b128 v[222:225], v126 offset:14464
	ds_read_b128 v[214:217], v126 offset:13952
	s_waitcnt vmcnt(0)
	v_alignbit_b32 v36, v75, v74, 16
	v_and_b32_e32 v41, 0xffff0000, v74
	s_xor_b32 s0, s11, 1
	v_lshlrev_b32_e32 v40, 16, v74
	v_and_b32_e32 v123, 0xffff0000, v75
	v_and_b32_e32 v122, 0xffff0000, v36
	s_mulk_i32 s0, 0x5400
	v_pk_mul_f32 v[34:35], v[0:1], v[40:41]
	v_pk_mul_f32 v[36:37], v[2:3], v[122:123]
	v_add_u32_e32 v130, s0, v79
	v_pk_mul_f32 v[120:121], v[78:79], v[34:35] op_sel_hi:[0,1]
	v_pk_mul_f32 v[128:129], v[78:79], v[36:37] op_sel_hi:[0,1]
	v_lshl_add_u32 v131, v50, 2, v130
	v_xor_b32_e32 v35, 0x80000000, v121
	v_xor_b32_e32 v34, 0x80000000, v120
	v_xor_b32_e32 v37, 0x80000000, v129
	v_xor_b32_e32 v36, 0x80000000, v128
	ds_write_b128 v131, v[34:37]
	v_alignbit_b32 v36, v77, v76, 16
	v_and_b32_e32 v45, 0xffff0000, v76
	v_lshlrev_b32_e32 v44, 16, v76
	v_and_b32_e32 v37, 0xffff0000, v77
	v_and_b32_e32 v36, 0xffff0000, v36
	v_pk_add_f32 v[34:35], v[44:45], 1.0 op_sel_hi:[1,0] neg_lo:[1,0] neg_hi:[1,0]
	v_pk_add_f32 v[36:37], v[36:37], 1.0 op_sel_hi:[1,0] neg_lo:[1,0] neg_hi:[1,0]
	ds_write_b128 v131, v[34:37] offset:256
	v_alignbit_b32 v36, v73, v72, 16
	v_and_b32_e32 v43, 0xffff0000, v72
	v_lshlrev_b32_e32 v42, 16, v72
	v_and_b32_e32 v45, 0xffff0000, v73
	v_and_b32_e32 v44, 0xffff0000, v36
	v_pk_mul_f32 v[34:35], v[120:121], v[42:43]
	v_pk_mul_f32 v[36:37], v[128:129], v[44:45]
	ds_write_b128 v131, v[34:37] offset:512
	v_pk_add_f32 v[34:35], v[42:43], -1.0 op_sel_hi:[1,0]
	v_pk_add_f32 v[36:37], v[44:45], -1.0 op_sel_hi:[1,0]
	v_pk_fma_f32 v[34:35], v[4:5], v[34:35], 1.0 op_sel_hi:[1,1,0]
	v_pk_fma_f32 v[36:37], v[6:7], v[36:37], 1.0 op_sel_hi:[1,1,0]
	v_pk_mul_f32 v[34:35], v[34:35], v[40:41]
	v_pk_mul_f32 v[36:37], v[36:37], v[122:123]
	ds_write_b128 v131, v[34:37] offset:768
	v_alignbit_b32 v34, v63, v62, 16
	v_and_b32_e32 v39, 0xffff0000, v62
	v_lshlrev_b32_e32 v38, 16, v62
	v_and_b32_e32 v41, 0xffff0000, v63
	v_and_b32_e32 v40, 0xffff0000, v34
	v_lshlrev_b32_e32 v34, 16, v102
	v_lshl_add_u32 v35, v48, 2, v130
	ds_write_b128 v131, v[38:41] offset:1024
	ds_write_b32 v35, v34 offset:1280
	s_waitcnt lgkmcnt(12)
	v_pk_mul_f32 v[250:251], v[8:9], v[184:185]
	v_pk_mul_f32 v[252:253], v[204:205], v[196:197] op_sel_hi:[0,1]
	v_pk_fma_f32 v[250:251], v[10:11], v[186:187], v[250:251]
	v_pk_mul_f32 v[254:255], v[204:205], v[198:199] op_sel_hi:[0,1]
	v_add_f32_e32 v14, v250, v251
	v_pk_fma_f32 v[252:253], v[8:9], v[188:189], v[252:253]
	v_pk_fma_f32 v[254:255], v[10:11], v[190:191], v[254:255]
	v_add_f32_dpp v14, v14, v14 quad_perm:[1,0,3,2] row_mask:0xf bank_mask:0xf bound_ctrl:1
	v_pk_mul_f32 v[12:13], v[8:9], v[244:245]
	ds_read_b32 v248, v124 offset:16064
	v_add_f32_dpp v14, v14, v14 quad_perm:[2,3,0,1] row_mask:0xf bank_mask:0xf bound_ctrl:1
	v_pk_fma_f32 v[12:13], v[10:11], v[246:247], v[12:13]
	ds_read_b128 v[228:231], v126 offset:14784
	v_add_f32_dpp v14, v14, v14 row_half_mirror row_mask:0xf bank_mask:0xf bound_ctrl:1
	v_add_f32_e32 v26, v12, v13
	ds_read_b128 v[240:243], v126 offset:15552
	v_add_f32_dpp v14, v14, v14 row_mirror row_mask:0xf bank_mask:0xf bound_ctrl:1
	v_pk_fma_f32 v[8:9], v[14:15], v[192:193], v[252:253] op_sel_hi:[0,1,1]
	v_pk_fma_f32 v[10:11], v[14:15], v[194:195], v[254:255] op_sel_hi:[0,1,1]
	ds_read_b128 v[232:235], v126 offset:15040
	ds_read_b128 v[244:247], v126 offset:15808
	ds_read_b128 v[236:239], v126 offset:15296
	s_waitcnt lgkmcnt(12)
	v_pk_mul_f32 v[250:251], v[8:9], v[206:207]
	v_pk_mul_f32 v[252:253], v[226:227], v[218:219] op_sel_hi:[0,1]
	v_pk_fma_f32 v[250:251], v[10:11], v[208:209], v[250:251]
	v_pk_mul_f32 v[254:255], v[226:227], v[220:221] op_sel_hi:[0,1]
	v_add_f32_e32 v14, v250, v251
	v_pk_fma_f32 v[252:253], v[8:9], v[210:211], v[252:253]
	v_pk_fma_f32 v[254:255], v[10:11], v[212:213], v[254:255]
	v_add_f32_dpp v14, v14, v14 quad_perm:[1,0,3,2] row_mask:0xf bank_mask:0xf bound_ctrl:1
	v_pk_mul_f32 v[12:13], v[8:9], v[200:201]
	ds_read_b32 v204, v124 offset:17408
	v_add_f32_dpp v14, v14, v14 quad_perm:[2,3,0,1] row_mask:0xf bank_mask:0xf bound_ctrl:1
	v_pk_fma_f32 v[12:13], v[10:11], v[202:203], v[12:13]
	ds_read_b128 v[184:187], v126 offset:16128
	v_add_f32_dpp v14, v14, v14 row_half_mirror row_mask:0xf bank_mask:0xf bound_ctrl:1
	v_add_f32_e32 v27, v12, v13
	ds_read_b128 v[196:199], v126 offset:16896
	v_add_f32_dpp v14, v14, v14 row_mirror row_mask:0xf bank_mask:0xf bound_ctrl:1
	v_pk_fma_f32 v[8:9], v[14:15], v[214:215], v[252:253] op_sel_hi:[0,1,1]
	v_pk_fma_f32 v[10:11], v[14:15], v[216:217], v[254:255] op_sel_hi:[0,1,1]
	ds_read_b128 v[188:191], v126 offset:16384
	ds_read_b128 v[200:203], v126 offset:17152
	ds_read_b128 v[192:195], v126 offset:16640
	s_waitcnt lgkmcnt(6)
	v_pk_mul_f32 v[250:251], v[8:9], v[228:229]
	v_pk_mul_f32 v[252:253], v[248:249], v[240:241] op_sel_hi:[0,1]
	v_pk_fma_f32 v[250:251], v[10:11], v[230:231], v[250:251]
	v_pk_mul_f32 v[254:255], v[248:249], v[242:243] op_sel_hi:[0,1]
	v_add_f32_e32 v14, v250, v251
	v_pk_fma_f32 v[252:253], v[8:9], v[232:233], v[252:253]
	v_pk_fma_f32 v[254:255], v[10:11], v[234:235], v[254:255]
	v_add_f32_dpp v14, v14, v14 quad_perm:[1,0,3,2] row_mask:0xf bank_mask:0xf bound_ctrl:1
	v_pk_mul_f32 v[12:13], v[8:9], v[222:223]
	ds_read_b32 v226, v124 offset:18752
	v_add_f32_dpp v14, v14, v14 quad_perm:[2,3,0,1] row_mask:0xf bank_mask:0xf bound_ctrl:1
	v_pk_fma_f32 v[12:13], v[10:11], v[224:225], v[12:13]
	ds_read_b128 v[206:209], v126 offset:17472
	v_add_f32_dpp v14, v14, v14 row_half_mirror row_mask:0xf bank_mask:0xf bound_ctrl:1
	v_add_f32_e32 v28, v12, v13
	ds_read_b128 v[218:221], v126 offset:18240
	v_add_f32_dpp v14, v14, v14 row_mirror row_mask:0xf bank_mask:0xf bound_ctrl:1
	v_pk_fma_f32 v[8:9], v[14:15], v[236:237], v[252:253] op_sel_hi:[0,1,1]
	v_pk_fma_f32 v[10:11], v[14:15], v[238:239], v[254:255] op_sel_hi:[0,1,1]
	ds_read_b128 v[210:213], v126 offset:17728
	ds_read_b128 v[222:225], v126 offset:18496
	ds_read_b128 v[214:217], v126 offset:17984
	s_waitcnt lgkmcnt(6)
	v_pk_mul_f32 v[250:251], v[8:9], v[184:185]
	v_pk_mul_f32 v[252:253], v[204:205], v[196:197] op_sel_hi:[0,1]
	v_pk_fma_f32 v[250:251], v[10:11], v[186:187], v[250:251]
	v_pk_mul_f32 v[254:255], v[204:205], v[198:199] op_sel_hi:[0,1]
	v_add_f32_e32 v14, v250, v251
	v_pk_fma_f32 v[252:253], v[8:9], v[188:189], v[252:253]
	v_pk_fma_f32 v[254:255], v[10:11], v[190:191], v[254:255]
	v_add_f32_dpp v14, v14, v14 quad_perm:[1,0,3,2] row_mask:0xf bank_mask:0xf bound_ctrl:1
	v_pk_mul_f32 v[12:13], v[8:9], v[244:245]
	ds_read_b32 v248, v124 offset:20096
	v_add_f32_dpp v14, v14, v14 quad_perm:[2,3,0,1] row_mask:0xf bank_mask:0xf bound_ctrl:1
	v_pk_fma_f32 v[12:13], v[10:11], v[246:247], v[12:13]
	ds_read_b128 v[228:231], v126 offset:18816
	v_add_f32_dpp v14, v14, v14 row_half_mirror row_mask:0xf bank_mask:0xf bound_ctrl:1
	v_add_f32_e32 v29, v12, v13
	ds_read_b128 v[240:243], v126 offset:19584
	v_add_f32_dpp v14, v14, v14 row_mirror row_mask:0xf bank_mask:0xf bound_ctrl:1
	v_pk_fma_f32 v[8:9], v[14:15], v[192:193], v[252:253] op_sel_hi:[0,1,1]
	v_pk_fma_f32 v[10:11], v[14:15], v[194:195], v[254:255] op_sel_hi:[0,1,1]
	ds_read_b128 v[232:235], v126 offset:19072
	ds_read_b128 v[244:247], v126 offset:19840
	ds_read_b128 v[236:239], v126 offset:19328
	s_waitcnt lgkmcnt(6)
	v_pk_mul_f32 v[250:251], v[8:9], v[206:207]
	v_pk_mul_f32 v[252:253], v[226:227], v[218:219] op_sel_hi:[0,1]
	v_pk_fma_f32 v[250:251], v[10:11], v[208:209], v[250:251]
	v_pk_mul_f32 v[254:255], v[226:227], v[220:221] op_sel_hi:[0,1]
	v_add_f32_e32 v14, v250, v251
	v_pk_fma_f32 v[252:253], v[8:9], v[210:211], v[252:253]
	v_pk_fma_f32 v[254:255], v[10:11], v[212:213], v[254:255]
	v_add_f32_dpp v14, v14, v14 quad_perm:[1,0,3,2] row_mask:0xf bank_mask:0xf bound_ctrl:1
	v_pk_mul_f32 v[12:13], v[8:9], v[200:201]
	ds_read_b32 v204, v124 offset:21440
	v_add_f32_dpp v14, v14, v14 quad_perm:[2,3,0,1] row_mask:0xf bank_mask:0xf bound_ctrl:1
	v_pk_fma_f32 v[12:13], v[10:11], v[202:203], v[12:13]
	ds_read_b128 v[184:187], v126 offset:20160
	v_add_f32_dpp v14, v14, v14 row_half_mirror row_mask:0xf bank_mask:0xf bound_ctrl:1
	v_add_f32_e32 v30, v12, v13
	ds_read_b128 v[196:199], v126 offset:20928
	v_add_f32_dpp v14, v14, v14 row_mirror row_mask:0xf bank_mask:0xf bound_ctrl:1
	v_pk_fma_f32 v[8:9], v[14:15], v[214:215], v[252:253] op_sel_hi:[0,1,1]
	v_pk_fma_f32 v[10:11], v[14:15], v[216:217], v[254:255] op_sel_hi:[0,1,1]
	ds_read_b128 v[188:191], v126 offset:20416
	ds_read_b128 v[200:203], v126 offset:21184
	ds_read_b128 v[192:195], v126 offset:20672
	s_waitcnt lgkmcnt(6)
	v_pk_mul_f32 v[250:251], v[8:9], v[228:229]
	v_pk_mul_f32 v[252:253], v[248:249], v[240:241] op_sel_hi:[0,1]
	v_pk_fma_f32 v[250:251], v[10:11], v[230:231], v[250:251]
	v_pk_mul_f32 v[254:255], v[248:249], v[242:243] op_sel_hi:[0,1]
	v_add_f32_e32 v14, v250, v251
	v_pk_fma_f32 v[252:253], v[8:9], v[232:233], v[252:253]
	v_pk_fma_f32 v[254:255], v[10:11], v[234:235], v[254:255]
	v_add_f32_dpp v14, v14, v14 quad_perm:[1,0,3,2] row_mask:0xf bank_mask:0xf bound_ctrl:1
	v_pk_mul_f32 v[12:13], v[8:9], v[222:223]
	s_nop 0
	v_add_f32_dpp v14, v14, v14 quad_perm:[2,3,0,1] row_mask:0xf bank_mask:0xf bound_ctrl:1
	v_pk_fma_f32 v[12:13], v[10:11], v[224:225], v[12:13]
	s_nop 0
	v_add_f32_dpp v14, v14, v14 row_half_mirror row_mask:0xf bank_mask:0xf bound_ctrl:1
	v_add_f32_e32 v31, v12, v13
	s_nop 0
	v_add_f32_dpp v14, v14, v14 row_mirror row_mask:0xf bank_mask:0xf bound_ctrl:1
	v_pk_fma_f32 v[8:9], v[14:15], v[236:237], v[252:253] op_sel_hi:[0,1,1]
	v_pk_fma_f32 v[10:11], v[14:15], v[238:239], v[254:255] op_sel_hi:[0,1,1]
	s_waitcnt lgkmcnt(0)
	v_pk_mul_f32 v[250:251], v[8:9], v[184:185]
	v_pk_mul_f32 v[252:253], v[204:205], v[196:197] op_sel_hi:[0,1]
	v_pk_fma_f32 v[250:251], v[10:11], v[186:187], v[250:251]
	v_pk_mul_f32 v[254:255], v[204:205], v[198:199] op_sel_hi:[0,1]
	v_add_f32_e32 v14, v250, v251
	v_pk_fma_f32 v[252:253], v[8:9], v[188:189], v[252:253]
	v_pk_fma_f32 v[254:255], v[10:11], v[190:191], v[254:255]
	v_add_f32_dpp v14, v14, v14 quad_perm:[1,0,3,2] row_mask:0xf bank_mask:0xf bound_ctrl:1
	v_pk_mul_f32 v[12:13], v[8:9], v[244:245]
	s_nop 0
	v_add_f32_dpp v14, v14, v14 quad_perm:[2,3,0,1] row_mask:0xf bank_mask:0xf bound_ctrl:1
	v_pk_fma_f32 v[12:13], v[10:11], v[246:247], v[12:13]
	s_nop 0
	v_add_f32_dpp v14, v14, v14 row_half_mirror row_mask:0xf bank_mask:0xf bound_ctrl:1
	v_add_f32_e32 v32, v12, v13
	s_nop 0
	v_add_f32_dpp v14, v14, v14 row_mirror row_mask:0xf bank_mask:0xf bound_ctrl:1
	v_pk_fma_f32 v[8:9], v[14:15], v[192:193], v[252:253] op_sel_hi:[0,1,1]
	v_pk_fma_f32 v[10:11], v[14:15], v[194:195], v[254:255] op_sel_hi:[0,1,1]
	v_pk_mul_f32 v[12:13], v[8:9], v[200:201]
	v_cndmask_b32_e64 v80, v26, v18, s[38:39]
	v_pk_fma_f32 v[12:13], v[10:11], v[202:203], v[12:13]
	v_cndmask_b32_e64 v121, v18, v26, s[38:39]
	v_add_f32_e32 v33, v12, v13
	v_cndmask_b32_e64 v82, v27, v19, s[38:39]
	v_cndmask_b32_e64 v122, v19, v27, s[38:39]
	v_cndmask_b32_e64 v83, v28, v20, s[38:39]
	v_cndmask_b32_e64 v123, v20, v28, s[38:39]
	v_cndmask_b32_e64 v84, v29, v21, s[38:39]
	v_cndmask_b32_e64 v125, v21, v29, s[38:39]
	v_cndmask_b32_e64 v85, v30, v22, s[38:39]
	v_cndmask_b32_e64 v127, v22, v30, s[38:39]
	v_cndmask_b32_e64 v86, v31, v23, s[38:39]
	v_cndmask_b32_e64 v128, v23, v31, s[38:39]
	v_cndmask_b32_e64 v103, v32, v24, s[38:39]
	v_cndmask_b32_e64 v129, v24, v32, s[38:39]
	v_cndmask_b32_e64 v120, v33, v25, s[38:39]
	v_cndmask_b32_e64 v130, v25, v33, s[38:39]
	v_add_f32_dpp v34, v121, v80 row_mirror row_mask:0xf bank_mask:0xf bound_ctrl:1
	v_add_f32_dpp v35, v122, v82 row_mirror row_mask:0xf bank_mask:0xf bound_ctrl:1
	v_add_f32_dpp v36, v123, v83 row_mirror row_mask:0xf bank_mask:0xf bound_ctrl:1
	v_add_f32_dpp v37, v125, v84 row_mirror row_mask:0xf bank_mask:0xf bound_ctrl:1
	v_add_f32_dpp v38, v127, v85 row_mirror row_mask:0xf bank_mask:0xf bound_ctrl:1
	v_add_f32_dpp v39, v128, v86 row_mirror row_mask:0xf bank_mask:0xf bound_ctrl:1
	v_add_f32_dpp v40, v129, v103 row_mirror row_mask:0xf bank_mask:0xf bound_ctrl:1
	v_add_f32_dpp v41, v130, v120 row_mirror row_mask:0xf bank_mask:0xf bound_ctrl:1
	v_cndmask_b32_e64 v80, v38, v34, s[40:41]
	v_cndmask_b32_e64 v121, v34, v38, s[40:41]
	v_cndmask_b32_e64 v82, v39, v35, s[40:41]
	v_cndmask_b32_e64 v122, v35, v39, s[40:41]
	v_cndmask_b32_e64 v83, v40, v36, s[40:41]
	v_cndmask_b32_e64 v123, v36, v40, s[40:41]
	v_cndmask_b32_e64 v84, v41, v37, s[40:41]
	v_cndmask_b32_e64 v125, v37, v41, s[40:41]
	v_add_f32_dpp v42, v121, v80 row_half_mirror row_mask:0xf bank_mask:0xf bound_ctrl:1
	v_add_f32_dpp v43, v122, v82 row_half_mirror row_mask:0xf bank_mask:0xf bound_ctrl:1
	v_add_f32_dpp v44, v123, v83 row_half_mirror row_mask:0xf bank_mask:0xf bound_ctrl:1
	v_add_f32_dpp v45, v125, v84 row_half_mirror row_mask:0xf bank_mask:0xf bound_ctrl:1
	v_cndmask_b32_e64 v80, v44, v42, s[42:43]
	v_cndmask_b32_e64 v121, v42, v44, s[42:43]
	v_cndmask_b32_e64 v82, v45, v43, s[42:43]
	v_cndmask_b32_e64 v122, v43, v45, s[42:43]
	v_add_u32_e32 v16, s6, v48
	s_mov_b64 s[0:1], -1
	v_add_f32_dpp v13, v121, v80 quad_perm:[2,3,0,1] row_mask:0xf bank_mask:0xf bound_ctrl:1
	v_add_f32_dpp v14, v122, v82 quad_perm:[2,3,0,1] row_mask:0xf bank_mask:0xf bound_ctrl:1
	s_cmp_gt_u32 s10, 15
	v_cndmask_b32_e64 v12, v13, v14, s[44:45]
	v_mov_b32_e32 v15, 0
	s_nop 1
	v_mov_b32_dpp v15, v12 quad_perm:[1,0,3,2] row_mask:0xf bank_mask:0xf
	s_cbranch_scc0 .LBB0_776
	v_add_u32_e32 v12, 0xffffff00, v16
	v_cndmask_b32_e64 v12, v101, v12, s[46:47]
	v_add_u32_e32 v12, v12, v98
	s_mov_b64 s[0:1], 0

	.amdhsa_kernel _Z14fwd_megakernel1P
		.amdhsa_group_segment_fixed_size 16
		.amdhsa_private_segment_fixed_size 0
		.amdhsa_kernarg_size 512
		.amdhsa_user_sgpr_count 2
		.amdhsa_user_sgpr_dispatch_ptr 0
		.amdhsa_user_sgpr_queue_ptr 0
		.amdhsa_user_sgpr_kernarg_segment_ptr 1
		.amdhsa_user_sgpr_dispatch_id 0
		.amdhsa_user_sgpr_kernarg_preload_length 0
		.amdhsa_user_sgpr_kernarg_preload_offset 0
		.amdhsa_user_sgpr_private_segment_size 0
		.amdhsa_uses_dynamic_stack 0
		.amdhsa_enable_private_segment 0
		.amdhsa_system_sgpr_workgroup_id_x 1
		.amdhsa_system_sgpr_workgroup_id_y 0
		.amdhsa_system_sgpr_workgroup_id_z 0
		.amdhsa_system_sgpr_workgroup_info 0
		.amdhsa_system_vgpr_workitem_id 2
		.amdhsa_next_free_vgpr 256
		.amdhsa_next_free_sgpr 100
		.amdhsa_accum_offset 256
		.amdhsa_reserve_vcc 1
		.amdhsa_float_round_mode_32 0
		.amdhsa_float_round_mode_16_64 0
		.amdhsa_float_denorm_mode_32 3
		.amdhsa_float_denorm_mode_16_64 3
		.amdhsa_dx10_clamp 1
		.amdhsa_ieee_mode 1
		.amdhsa_fp16_overflow 0
		.amdhsa_tg_split 0
		.amdhsa_exception_fp_ieee_invalid_op 0
		.amdhsa_exception_fp_denorm_src 0
		.amdhsa_exception_fp_ieee_div_zero 0
		.amdhsa_exception_fp_ieee_overflow 0
		.amdhsa_exception_fp_ieee_underflow 0
		.amdhsa_exception_fp_ieee_inexact 0
		.amdhsa_exception_int_div_zero 0
	.end_amdhsa_kernel

amdhsa.kernels:
  - .agpr_count:     0
    .args:
      - .offset:         0
        .size:           256
        .value_kind:     by_value
      - .offset:         256
        .size:           4
        .value_kind:     hidden_block_count_x
      - .offset:         260
        .size:           4
        .value_kind:     hidden_block_count_y
      - .offset:         264
        .size:           4
        .value_kind:     hidden_block_count_z
      - .offset:         268
        .size:           2
        .value_kind:     hidden_group_size_x
      - .offset:         270
        .size:           2
        .value_kind:     hidden_group_size_y
      - .offset:         272
        .size:           2
        .value_kind:     hidden_group_size_z
      - .offset:         274
        .size:           2
        .value_kind:     hidden_remainder_x
      - .offset:         276
        .size:           2
        .value_kind:     hidden_remainder_y
      - .offset:         278
        .size:           2
        .value_kind:     hidden_remainder_z
      - .offset:         296
        .size:           8
        .value_kind:     hidden_global_offset_x
      - .offset:         304
        .size:           8
        .value_kind:     hidden_global_offset_y
      - .offset:         312
        .size:           8
        .value_kind:     hidden_global_offset_z
      - .offset:         320
        .size:           2
        .value_kind:     hidden_grid_dims
      - .offset:         344
        .size:           8
        .value_kind:     hidden_multigrid_sync_arg
      - .offset:         376
        .size:           4
        .value_kind:     hidden_dynamic_lds_size
    .group_segment_fixed_size: 16
    .kernarg_segment_align: 8
    .kernarg_segment_size: 512
    .language:       OpenCL C
    .language_version:
      - 2
      - 0
    .max_flat_workgroup_size: 256
    .name:           _Z14fwd_megakernel1P
    .private_segment_fixed_size: 0
    .sgpr_count:     106
    .sgpr_spill_count: 222
    .symbol:         _Z14fwd_megakernel1P.kd
    .uniform_work_group_size: 1
    .uses_dynamic_stack: false
    .vgpr_count:     256
    .vgpr_spill_count: 0
    .wavefront_size: 64
